# P7/P8 stagger applied to CU pairs (vcu bit 1) instead of odd CUs (bit 0)
# baseline (speedup 1.0000x reference)
.LBB0_1401:
	s_cmpk_lt_i32 s62, 0x408
	s_cselect_b64 s[4:5], -1, 0
	s_bitcmp1_b32 s62, 1
	s_cselect_b64 s[0:1], -1, 0
	s_and_b64 vcc, exec, s[0:1]
	s_cbranch_vccz .LBB0_1404
	s_cmp_lt_u32 s62, 8
	s_cbranch_scc1 .LBB0_1404
	s_mov_b32 s0, 4
	s_cmp_lt_i32 s0, 1
	s_cbranch_scc1 .LBB0_1404

.LBB0_1482:
	s_or_b64 exec, exec, s[36:37]
	s_waitcnt lgkmcnt(0)
	s_barrier
	s_bitcmp0_b32 s62, 1
	s_cbranch_scc1 .LBB0_1485
	s_cmp_lt_u32 s62, 8
	s_cbranch_scc1 .LBB0_1485
	s_mov_b32 s0, 4
	s_cmp_lt_i32 s0, 1
	s_cbranch_scc1 .LBB0_1485
